# lever 7 instruction selection: contract mul+add into v_fma_f32 in the P3 sum-of-squares chains (88 fewer VALU per P3 iteration)
# speedup vs baseline: 1.0353x; 1.0008x over previous
; DI void phase3(const Params& p, char* smem, const Sched sc) {
;     ...
;       const float rstd = rsqrtf(sumsq[tl] * (1.f / 384) + 1e-6f);
;       float ssq = 0.f;
; #pragma unroll
;       for (int rb = 0; rb < 3; ++rb)
; #pragma unroll
;         for (int i = 0; i < 16; ++i) { const float v = acc[rb][0][i] * rstd; acc[rb][0][i] = v; ssq += v * v; }
;       ssq += other_half(ssq);
;       const float r2 = rsqrtf(ssq * (1.f / 96) + 1e-6f);
; #pragma unroll
;       for (int rb = 0; rb < 3; ++rb)
; #pragma unroll
;         for (int g = 0; g < 4; ++g) {
;           const f32x4 w4 = *(const f32x4*)(p.qhn + rb * 32 + 8 * g + 4 * h);
; #pragma unroll
;           for (int e = 0; e < 4; ++e) acc[rb][0][4 * g + e] *= r2 * w4[e];
;         }
; #pragma unroll
;       for (int g = 0; g < 2; ++g) {
;         const f32x4 c4 = *(const f32x4*)(p.cosT + (size_t)token * 16 + 8 * g + 4 * h), s4 = *(const f32x4*)(p.sinT + (size_t)token * 16 + 8 * g + 4 * h);
.LBB0_358:
	s_or_b64 exec, exec, s[4:5]
	s_waitcnt lgkmcnt(0)
	s_barrier
	ds_read_b32 v48, v231
	global_load_dwordx4 v[64:67], v[202:203], off
	global_load_dwordx4 v[68:71], v[202:203], off offset:32
	global_load_dwordx4 v[72:75], v[202:203], off offset:64
	global_load_dwordx4 v[76:79], v[202:203], off offset:96
	global_load_dwordx4 v[80:83], v[202:203], off offset:128
	global_load_dwordx4 v[84:87], v[202:203], off offset:160
	global_load_dwordx4 v[88:91], v[202:203], off offset:192
	global_load_dwordx4 v[92:95], v[202:203], off offset:224
	global_load_dwordx4 v[96:99], v[202:203], off offset:256
	global_load_dwordx4 v[100:103], v[202:203], off offset:288
	global_load_dwordx4 v[104:107], v[202:203], off offset:320
	global_load_dwordx4 v[108:111], v[202:203], off offset:352
	v_ashrrev_i32_e32 v209, 31, v208
	v_lshl_or_b32 v120, v240, 3, s25
	v_ashrrev_i32_e32 v121, 31, v120
	s_waitcnt lgkmcnt(0)
	v_fmamk_f32 v48, v48, 0x3b2aaaab, v233
	v_mul_f32_e32 v49, 0x4b800000, v48
	v_cmp_gt_f32_e32 vcc, s19, v48
	v_lshlrev_b64 v[120:121], 13, v[120:121]
	v_or_b32_e32 v120, v120, v239
	v_cndmask_b32_e32 v48, v48, v49, vcc
	v_rsq_f32_e32 v48, v48
	s_nop 0
	v_mul_f32_e32 v49, 0x45800000, v48
	v_cndmask_b32_e32 v112, v48, v49, vcc
	v_mul_f32_e64 v32, v32, v112
	v_mul_f32_e64 v33, v33, v112
	v_mul_f32_e64 v34, v34, v112
	v_mul_f32_e64 v35, v35, v112
	s_nop 0
	v_mul_f32_e64 v137, v33, v33
	s_nop 0
	s_nop 0
	v_fma_f32 v136, v32, v32, v137
	v_mul_f32_e64 v36, v36, v112
	v_mul_f32_e64 v37, v37, v112
	v_fma_f32 v134, v34, v34, v136
	s_nop 0
	s_nop 0
	v_fma_f32 v134, v35, v35, v134
	v_mul_f32_e64 v60, v10, v112
	v_mul_f32_e64 v61, v11, v112
	v_lshlrev_b64 v[10:11], 6, v[208:209]
	v_mul_f32_e64 v38, v38, v112
	v_mul_f32_e64 v39, v39, v112
	v_fma_f32 v132, v36, v36, v134
	v_mul_f32_e64 v62, v12, v112
	v_mul_f32_e64 v63, v13, v112
	v_lshl_add_u64 v[12:13], v[192:193], 0, v[10:11]
	v_lshl_add_u64 v[48:49], v[194:195], 0, v[10:11]
	s_nop 0
	s_nop 0
	v_fma_f32 v132, v37, v37, v132
	global_load_dwordx4 v[52:55], v[12:13], off
	s_nop 0
	global_load_dwordx4 v[10:13], v[12:13], off offset:32
	s_nop 0
	global_load_dwordx4 v[56:59], v[48:49], off
	s_nop 0
	global_load_dwordx4 v[48:51], v[48:49], off offset:32
	v_mul_f32_e64 v40, v40, v112
	v_mul_f32_e64 v41, v41, v112
	v_fma_f32 v130, v38, v38, v132
	s_nop 0
	s_nop 0
	v_fma_f32 v130, v39, v39, v130
	v_mul_f32_e64 v42, v42, v112
	v_mul_f32_e64 v43, v43, v112
	v_fma_f32 v128, v40, v40, v130
	s_nop 0
	s_nop 0
	v_fma_f32 v128, v41, v41, v128
	v_mul_f32_e64 v44, v44, v112
	v_mul_f32_e64 v45, v45, v112
	v_fma_f32 v126, v42, v42, v128
	s_nop 0
	s_nop 0
	v_fma_f32 v126, v43, v43, v126
	v_mul_f32_e64 v46, v46, v112
	v_mul_f32_e64 v47, v47, v112
	v_fma_f32 v124, v44, v44, v126
	s_nop 0
	s_nop 0
	v_fma_f32 v124, v45, v45, v124
	v_mul_f32_e64 v16, v16, v112
	v_mul_f32_e64 v17, v17, v112
	v_fma_f32 v122, v46, v46, v124
	s_nop 0
	s_nop 0
	v_fma_f32 v122, v47, v47, v122
	v_mul_f32_e64 v18, v18, v112
	v_mul_f32_e64 v19, v19, v112
	v_fma_f32 v122, v16, v16, v122
	s_nop 0
	s_nop 0
	v_fma_f32 v122, v17, v17, v122
	v_mul_f32_e64 v20, v20, v112
	v_mul_f32_e64 v21, v21, v112
	v_fma_f32 v122, v18, v18, v122
	s_nop 0
	s_nop 0
	v_fma_f32 v122, v19, v19, v122
	v_mul_f32_e64 v22, v22, v112
	v_mul_f32_e64 v23, v23, v112
	v_fma_f32 v122, v20, v20, v122
	s_nop 0
	s_nop 0
	v_fma_f32 v122, v21, v21, v122
	v_mul_f32_e64 v24, v24, v112
	v_mul_f32_e64 v25, v25, v112
	v_fma_f32 v122, v22, v22, v122
	s_nop 0
	s_nop 0
	v_fma_f32 v122, v23, v23, v122
	v_mul_f32_e64 v26, v26, v112
	v_mul_f32_e64 v27, v27, v112
	v_fma_f32 v122, v24, v24, v122
	s_nop 0
	s_nop 0
	v_fma_f32 v122, v25, v25, v122
	v_mul_f32_e64 v28, v28, v112
	v_mul_f32_e64 v29, v29, v112
	v_fma_f32 v122, v26, v26, v122
	s_nop 0
	s_nop 0
	v_fma_f32 v122, v27, v27, v122
	v_mul_f32_e64 v30, v30, v112
	v_mul_f32_e64 v31, v31, v112
	v_fma_f32 v122, v28, v28, v122
	s_nop 0
	s_nop 0
	v_fma_f32 v122, v29, v29, v122
	v_mul_f32_e64 v0, v0, v112
	v_mul_f32_e64 v1, v1, v112
	v_fma_f32 v122, v30, v30, v122
	s_nop 0
	s_nop 0
	v_fma_f32 v122, v31, v31, v122
	v_mul_f32_e64 v2, v2, v112
	v_mul_f32_e64 v3, v3, v112
	v_fma_f32 v122, v0, v0, v122
	s_nop 0
	s_nop 0
	v_fma_f32 v122, v1, v1, v122
	v_mul_f32_e64 v4, v4, v112
	v_mul_f32_e64 v5, v5, v112
	v_fma_f32 v122, v2, v2, v122
	s_nop 0
	s_nop 0
	v_fma_f32 v122, v3, v3, v122
	v_mul_f32_e64 v6, v6, v112
	v_mul_f32_e64 v7, v7, v112
	v_fma_f32 v122, v4, v4, v122
	s_nop 0
	s_nop 0
	v_fma_f32 v122, v5, v5, v122
	v_mul_f32_e64 v8, v8, v112
	v_mul_f32_e64 v9, v9, v112
	v_fma_f32 v122, v6, v6, v122
	v_mul_f32_e64 v14, v14, v112
	v_mul_f32_e64 v15, v15, v112
	s_nop 0
	s_nop 0
	v_fma_f32 v122, v7, v7, v122
	v_fma_f32 v112, v8, v8, v122
	s_nop 0
	s_nop 0
	v_fma_f32 v112, v9, v9, v112
	v_fma_f32 v112, v60, v60, v112
	s_nop 0
	s_nop 0
	v_fma_f32 v112, v61, v61, v112
	v_fma_f32 v112, v62, v62, v112
	s_nop 0
	s_nop 0
	v_fma_f32 v112, v63, v63, v112
	v_fma_f32 v112, v14, v14, v112
	v_fma_f32 v112, v15, v15, v112
	v_mov_b32_e32 v113, v112
	v_mov_b32_e32 v114, v112
	s_nop 1
	v_permlane32_swap_b32_e32 v113, v114
	v_cndmask_b32_e64 v113, v113, v114, s[8:9]
	v_add_f32_e32 v112, v112, v113
	v_fmamk_f32 v112, v112, 0x3c2aaaab, v233
	v_mul_f32_e32 v113, 0x4b800000, v112
	v_cmp_gt_f32_e32 vcc, s19, v112
	s_nop 1
	v_cndmask_b32_e32 v112, v112, v113, vcc
	v_rsq_f32_e32 v114, v112
	v_mad_u64_u32 v[112:113], s[4:5], v120, s20, v[204:205]
	v_mad_i32_i24 v113, v121, s20, v113
	v_mul_f32_e32 v115, 0x45800000, v114
	v_cndmask_b32_e32 v114, v114, v115, vcc
	s_waitcnt vmcnt(15)
; DI unsigned pk_bf16(float lo, float hi) { f32x2 v = {lo, hi}; bf2_t b = __builtin_convertvector(v, bf2_t); return __builtin_bit_cast(unsigned, b); }
; DI void phase3(const Params& p, char* smem, const Sched sc) {
;     ...
; #pragma unroll
;       for (int rb = 0; rb < 3; ++rb)
; #pragma unroll
;         for (int g = 0; g < 4; ++g) {
;           const f32x4 w4 = *(const f32x4*)(p.qhn + rb * 32 + 8 * g + 4 * h);
; #pragma unroll
;           for (int e = 0; e < 4; ++e) acc[rb][0][4 * g + e] *= r2 * w4[e];
;         }
; #pragma unroll
;       for (int g = 0; g < 2; ++g) {
;         const f32x4 c4 = *(const f32x4*)(p.cosT + (size_t)token * 16 + 8 * g + 4 * h), s4 = *(const f32x4*)(p.sinT + (size_t)token * 16 + 8 * g + 4 * h);
; #pragma unroll
;         for (int e = 0; e < 4; ++e) {
;           const float x1 = acc[2][0][4 * g + e], x2 = acc[2][0][4 * (g + 2) + e];
;           acc[2][0][4 * g + e] = x1 * c4[e] - x2 * s4[e];
;           acc[2][0][4 * (g + 2) + e] = x2 * c4[e] + x1 * s4[e];
;         }
;       }
;       const float qs = LOG2E * 0.10206207261596577f;
;       bf16_t* dst = p.Qm + ((size_t)(b * 8 + head) * S_ + s) * 96;
; #pragma unroll
;       for (int rb = 0; rb < 3; ++rb) {
;         u32x2 w[4];
; #pragma unroll
;         for (int g = 0; g < 4; ++g) { w[g].x = pk_bf16(acc[rb][0][4 * g] * qs, acc[rb][0][4 * g + 1] * qs); w[g].y = pk_bf16(acc[rb][0][4 * g + 2] * qs, acc[rb][0][4 * g + 3] * qs); }
; #pragma unroll
;         for (int q = 0; q < 2; ++q) *(u32x4*)(dst + rb * 32 + 16 * q + 8 * h) = widen_pair(w[2 * q], w[2 * q + 1]);
;       }
	v_mul_f32_e64 v64, v64, v114
	v_mul_f32_e64 v65, v65, v114
	s_nop 0
	v_mul_f32_e64 v32, v32, v64
	v_mul_f32_e64 v33, v33, v65
	v_mul_f32_e64 v64, v66, v114
	v_mul_f32_e64 v65, v67, v114
	s_nop 0
	v_mul_f32_e64 v34, v34, v64
	v_mul_f32_e64 v35, v35, v65
	s_waitcnt vmcnt(14)
	v_mul_f32_e64 v64, v68, v114
	v_mul_f32_e64 v65, v69, v114
	s_nop 0
	v_mul_f32_e64 v36, v36, v64
	v_mul_f32_e64 v37, v37, v65
	v_mul_f32_e64 v64, v70, v114
	v_mul_f32_e64 v65, v71, v114
	s_nop 0
	v_mul_f32_e64 v38, v38, v64
	v_mul_f32_e64 v39, v39, v65
	s_waitcnt vmcnt(13)
	v_mul_f32_e64 v64, v72, v114
	v_mul_f32_e64 v65, v73, v114
	s_nop 0
	v_mul_f32_e64 v40, v40, v64
	v_mul_f32_e64 v41, v41, v65
	v_mul_f32_e64 v64, v74, v114
	v_mul_f32_e64 v65, v75, v114
	s_nop 0
	v_mul_f32_e64 v42, v42, v64
	v_mul_f32_e64 v43, v43, v65
	s_waitcnt vmcnt(12)
	v_mul_f32_e64 v64, v76, v114
	v_mul_f32_e64 v65, v77, v114
	s_nop 0
	v_mul_f32_e64 v44, v44, v64
	v_mul_f32_e64 v45, v45, v65
	v_mul_f32_e64 v64, v78, v114
	v_mul_f32_e64 v65, v79, v114
	s_nop 0
	v_mul_f32_e64 v46, v46, v64
	v_mul_f32_e64 v47, v47, v65
	s_waitcnt vmcnt(11)
	v_mul_f32_e64 v64, v80, v114
	v_mul_f32_e64 v65, v81, v114
	s_nop 0
	v_mul_f32_e64 v16, v16, v64
	v_mul_f32_e64 v17, v17, v65
	v_mul_f32_e64 v64, v82, v114
	v_mul_f32_e64 v65, v83, v114
	s_nop 0
	v_mul_f32_e64 v18, v18, v64
	v_mul_f32_e64 v19, v19, v65
	s_waitcnt vmcnt(10)
	v_mul_f32_e64 v64, v84, v114
	v_mul_f32_e64 v65, v85, v114
	s_nop 0
	v_mul_f32_e64 v20, v20, v64
	v_mul_f32_e64 v21, v21, v65
	v_mul_f32_e64 v64, v86, v114
	v_mul_f32_e64 v65, v87, v114
	s_nop 0
	v_mul_f32_e64 v22, v22, v64
	v_mul_f32_e64 v23, v23, v65
	s_waitcnt vmcnt(9)
	v_mul_f32_e64 v64, v88, v114
	v_mul_f32_e64 v65, v89, v114
	s_nop 0
	v_mul_f32_e64 v24, v24, v64
	v_mul_f32_e64 v25, v25, v65
	v_mul_f32_e64 v64, v90, v114
	v_mul_f32_e64 v65, v91, v114
	s_nop 0
	v_mul_f32_e64 v26, v26, v64
	v_mul_f32_e64 v27, v27, v65
	s_waitcnt vmcnt(8)
	v_mul_f32_e64 v64, v92, v114
	v_mul_f32_e64 v65, v93, v114
	s_nop 0
	v_mul_f32_e64 v28, v28, v64
	v_mul_f32_e64 v29, v29, v65
	v_mul_f32_e64 v64, v94, v114
	v_mul_f32_e64 v65, v95, v114
	s_nop 0
	v_mul_f32_e64 v30, v30, v64
	v_mul_f32_e64 v31, v31, v65
	s_waitcnt vmcnt(7)
	v_mul_f32_e64 v64, v96, v114
	v_mul_f32_e64 v65, v97, v114
	s_nop 0
	v_mul_f32_e64 v64, v0, v64
	v_mul_f32_e64 v65, v1, v65
	v_mul_f32_e64 v0, v98, v114
	v_mul_f32_e64 v1, v99, v114
	s_nop 0
	v_mul_f32_e64 v66, v2, v0
	v_mul_f32_e64 v67, v3, v1
	s_waitcnt vmcnt(6)
	v_mul_f32_e64 v0, v100, v114
	v_mul_f32_e64 v1, v101, v114
	v_mul_f32_e64 v2, v34, s2
	v_mul_f32_e64 v3, v35, s2
	v_mul_f32_e64 v68, v4, v0
	v_mul_f32_e64 v69, v5, v1
	v_mul_f32_e64 v0, v102, v114
	v_mul_f32_e64 v1, v103, v114
	v_mul_f32_e64 v4, v38, s2
	v_mul_f32_e64 v5, v39, s2
	v_mul_f32_e64 v70, v6, v0
	v_mul_f32_e64 v71, v7, v1
	s_waitcnt vmcnt(5)
	v_mul_f32_e64 v0, v104, v114
	v_mul_f32_e64 v1, v105, v114
	v_mul_f32_e64 v6, v42, s2
	v_mul_f32_e64 v7, v43, s2
	v_mul_f32_e64 v8, v8, v0
	v_mul_f32_e64 v9, v9, v1
	v_mul_f32_e64 v0, v106, v114
	v_mul_f32_e64 v1, v107, v114
	s_nop 0
	v_mul_f32_e64 v60, v60, v0
	v_mul_f32_e64 v61, v61, v1
	s_waitcnt vmcnt(4)
	v_mul_f32_e64 v0, v108, v114
	v_mul_f32_e64 v1, v109, v114
	s_nop 0
	v_mul_f32_e64 v62, v62, v0
	v_mul_f32_e64 v63, v63, v1
	v_mul_f32_e64 v0, v110, v114
	v_mul_f32_e64 v1, v111, v114
	s_nop 0
	v_mul_f32_e64 v14, v14, v0
	v_mul_f32_e64 v15, v15, v1
	s_waitcnt vmcnt(1)
	v_mul_f32_e64 v0, v56, v64
	v_mul_f32_e64 v1, v57, v65
	s_nop 0
	v_fma_f32 v72, v52, v8, v0
	v_fma_f32 v73, v53, v9, v1
	v_mul_f32_e64 v0, v58, v66
	v_mul_f32_e64 v1, v59, v67
	s_nop 0
	v_fma_f32 v74, v54, v60, v0
	v_fma_f32 v75, v55, v61, v1
	s_waitcnt vmcnt(0)
	v_mul_f32_e64 v0, v48, v68
	v_mul_f32_e64 v1, v49, v69
	s_nop 0
	v_fma_f32 v76, v10, v62, v0
	v_fma_f32 v77, v11, v63, v1
	v_mul_f32_e64 v0, v50, v70
	v_mul_f32_e64 v1, v51, v71
	s_nop 0
	v_fma_f32 v78, v12, v14, v0
	v_fma_f32 v79, v13, v15, v1
	v_mul_f32_e64 v0, v32, s2
	v_mul_f32_e64 v1, v33, s2
	v_mul_f32_e64 v32, v46, s2
	v_mul_f32_e64 v33, v47, s2
	v_cvt_pk_bf16_f32 v0, v0, v1
	v_cvt_pk_bf16_f32 v1, v2, v3
	v_mul_f32_e64 v2, v36, s2
	v_mul_f32_e64 v3, v37, s2
	s_nop 0
	v_cvt_pk_bf16_f32 v2, v2, v3
	v_cvt_pk_bf16_f32 v3, v4, v5
	v_mul_f32_e64 v4, v40, s2
	v_mul_f32_e64 v5, v41, s2
	v_permlane32_swap_b32_e32 v0, v2
	v_cvt_pk_bf16_f32 v4, v4, v5
	v_cvt_pk_bf16_f32 v5, v6, v7
	v_mul_f32_e64 v6, v44, s2
	v_mul_f32_e64 v7, v45, s2
	v_permlane32_swap_b32_e32 v1, v3
	v_cvt_pk_bf16_f32 v6, v6, v7
	v_cvt_pk_bf16_f32 v7, v32, v33
	global_store_dwordx4 v[112:113], v[0:3], off
	v_permlane32_swap_b32_e32 v4, v6
	v_permlane32_swap_b32_e32 v5, v7
	v_mul_f32_e64 v0, v16, s2
	v_mul_f32_e64 v1, v17, s2
	v_mul_f32_e64 v2, v18, s2
	v_mul_f32_e64 v3, v19, s2
	global_store_dwordx4 v[112:113], v[4:7], off offset:32
	v_cvt_pk_bf16_f32 v0, v0, v1
	v_cvt_pk_bf16_f32 v1, v2, v3
	v_mul_f32_e64 v2, v20, s2
	v_mul_f32_e64 v3, v21, s2
	v_mul_f32_e64 v4, v22, s2
	v_mul_f32_e64 v5, v23, s2
	v_cvt_pk_bf16_f32 v2, v2, v3
	v_cvt_pk_bf16_f32 v3, v4, v5
	v_mul_f32_e64 v4, v24, s2
	v_mul_f32_e64 v5, v25, s2
	v_mul_f32_e64 v6, v26, s2
	v_mul_f32_e64 v7, v27, s2
	v_permlane32_swap_b32_e32 v0, v2
	v_permlane32_swap_b32_e32 v1, v3
	v_cvt_pk_bf16_f32 v4, v4, v5
	v_cvt_pk_bf16_f32 v5, v6, v7
	v_mul_f32_e64 v6, v28, s2
	v_mul_f32_e64 v7, v29, s2
	v_mul_f32_e64 v16, v30, s2
	v_mul_f32_e64 v17, v31, s2
	global_store_dwordx4 v[112:113], v[0:3], off offset:64
	v_cvt_pk_bf16_f32 v6, v6, v7
	v_cvt_pk_bf16_f32 v7, v16, v17
	v_mul_f32_e64 v0, v56, v8
	v_mul_f32_e64 v1, v57, v9
	v_mul_f32_e64 v2, v58, v60
	v_mul_f32_e64 v3, v59, v61
	v_fma_f32 v0, v52, v64, -v0
	v_fma_f32 v1, v53, v65, -v1
	v_fma_f32 v2, v54, v66, -v2
	v_fma_f32 v3, v55, v67, -v3
	v_permlane32_swap_b32_e32 v4, v6
	v_permlane32_swap_b32_e32 v5, v7
	v_mul_f32_e64 v0, v0, s2
	v_mul_f32_e64 v1, v1, s2
	v_mul_f32_e64 v2, v2, s2
	v_mul_f32_e64 v3, v3, s2
	global_store_dwordx4 v[112:113], v[4:7], off offset:96
	v_cvt_pk_bf16_f32 v0, v0, v1
	v_cvt_pk_bf16_f32 v1, v2, v3
	v_mul_f32_e64 v2, v48, v62
	v_mul_f32_e64 v3, v49, v63
	v_mul_f32_e64 v4, v50, v14
	v_mul_f32_e64 v5, v51, v15
	v_fma_f32 v2, v10, v68, -v2
	v_fma_f32 v3, v11, v69, -v3
	v_fma_f32 v4, v12, v70, -v4
	v_fma_f32 v5, v13, v71, -v5
	v_mul_f32_e64 v2, v2, s2
	v_mul_f32_e64 v3, v3, s2
	v_mul_f32_e64 v4, v4, s2
	v_mul_f32_e64 v5, v5, s2
	v_cvt_pk_bf16_f32 v2, v2, v3
	v_cvt_pk_bf16_f32 v3, v4, v5
	v_mul_f32_e64 v4, v72, s2
	v_mul_f32_e64 v5, v73, s2
	v_mul_f32_e64 v6, v74, s2
	v_mul_f32_e64 v7, v75, s2
	v_cvt_pk_bf16_f32 v4, v4, v5
	v_cvt_pk_bf16_f32 v5, v6, v7
	v_mul_f32_e64 v6, v76, s2
	v_mul_f32_e64 v7, v77, s2
	v_mul_f32_e64 v8, v78, s2
	v_mul_f32_e64 v9, v79, s2
	v_cvt_pk_bf16_f32 v6, v6, v7
	v_cvt_pk_bf16_f32 v7, v8, v9
	v_permlane32_swap_b32_e32 v0, v2
	v_permlane32_swap_b32_e32 v1, v3
	v_permlane32_swap_b32_e32 v4, v6
	v_permlane32_swap_b32_e32 v5, v7
	global_store_dwordx4 v[112:113], v[0:3], off offset:128
	global_store_dwordx4 v[112:113], v[4:7], off offset:160

; DI void phase3(const Params& p, char* smem, const Sched sc) {
;     ...
;       const float rstd = rsqrtf(sumsq[tl] * (1.f / 256) + 1e-6f);
;       float kr[16];
; #pragma unroll
;       for (int g = 0; g < 4; ++g) {
;         const f32x4 k4 = *(const f32x4*)(p.KR + (size_t)token * 32 + 8 * g + 4 * h);
; #pragma unroll
;         for (int e = 0; e < 4; ++e) kr[4 * g + e] = k4[e];
;       }
;       float ssq = 0.f;
; #pragma unroll
;       for (int rb = 0; rb < 2; ++rb)
; #pragma unroll
;         for (int i = 0; i < 16; ++i) { const float v = acc[rb][0][i] * rstd; acc[rb][0][i] = v; ssq += v * v; }
; #pragma unroll
;       for (int i = 0; i < 16; ++i) ssq += kr[i] * kr[i];
;       ssq += other_half(ssq);
;       const float r2 = rsqrtf(ssq * (1.f / 96) + 1e-6f);
; #pragma unroll
;       for (int rb = 0; rb < 2; ++rb)
; #pragma unroll
;         for (int g = 0; g < 4; ++g) {
;           const f32x4 w4 = *(const f32x4*)(p.khn + rb * 32 + 8 * g + 4 * h);
; #pragma unroll
;           for (int e = 0; e < 4; ++e) acc[rb][0][4 * g + e] *= r2 * w4[e];
.LBB0_370:
	s_or_b64 exec, exec, s[12:13]
	v_ashrrev_i32_e32 v209, 31, v208
	s_waitcnt lgkmcnt(0)
	v_lshlrev_b64 v[64:65], 7, v[208:209]
	v_lshl_add_u64 v[92:93], v[188:189], 0, v[64:65]
	s_barrier
	global_load_dwordx4 v[68:71], v[92:93], off offset:32
	global_load_dwordx4 v[72:75], v[92:93], off offset:64
	global_load_dwordx4 v[64:67], v[92:93], off offset:96
	ds_read_b32 v94, v231
	global_load_dwordx4 v[88:91], v[190:191], off
	global_load_dwordx4 v[84:87], v[190:191], off offset:32
	global_load_dwordx4 v[80:83], v[190:191], off offset:64
	global_load_dwordx4 v[76:79], v[190:191], off offset:96
	global_load_dwordx4 v[104:107], v[190:191], off offset:128
	global_load_dwordx4 v[96:99], v[190:191], off offset:160
	s_waitcnt lgkmcnt(0)
	v_fmamk_f32 v94, v94, 0x3b800000, v233
	v_mul_f32_e32 v95, 0x4b800000, v94
	v_cmp_gt_f32_e32 vcc, s19, v94
	s_waitcnt vmcnt(8)
	s_nop 0
	s_nop 0
	v_cndmask_b32_e32 v94, v94, v95, vcc
	v_rsq_f32_e32 v112, v94
	global_load_dwordx4 v[92:95], v[92:93], off
	s_nop 0
	global_load_dwordx4 v[108:111], v[190:191], off offset:192
	global_load_dwordx4 v[100:103], v[190:191], off offset:224
	s_waitcnt vmcnt(10)
	s_nop 0
	s_nop 0
	s_nop 0
	s_nop 0
	v_mul_f32_e32 v113, 0x45800000, v112
	v_cndmask_b32_e32 v112, v112, v113, vcc
	v_mul_f32_e64 v132, v48, v112
	v_mul_f32_e64 v133, v49, v112
	v_mul_f32_e64 v130, v50, v112
	v_mul_f32_e64 v131, v51, v112
	s_nop 0
	v_mul_f32_e64 v51, v133, v133
	s_nop 0
	s_nop 0
	v_fma_f32 v50, v132, v132, v51
	v_mul_f32_e64 v128, v52, v112
	v_mul_f32_e64 v129, v53, v112
	v_fma_f32 v48, v130, v130, v50
	v_mul_f32_e64 v134, v42, v112
	v_mul_f32_e64 v135, v43, v112
	s_nop 0
	s_nop 0
	v_fma_f32 v48, v131, v131, v48
	v_mul_f32_e64 v126, v54, v112
	v_mul_f32_e64 v127, v55, v112
	v_fma_f32 v42, v128, v128, v48
	v_mul_f32_e64 v136, v40, v112
	v_mul_f32_e64 v137, v41, v112
	s_nop 0
	s_nop 0
	v_fma_f32 v42, v129, v129, v42
	v_mul_f32_e64 v124, v56, v112
	v_mul_f32_e64 v125, v57, v112
	v_fma_f32 v40, v126, v126, v42
	v_mul_f32_e64 v138, v38, v112
	v_mul_f32_e64 v139, v39, v112
	s_nop 0
	s_nop 0
	v_fma_f32 v40, v127, v127, v40
	v_mul_f32_e64 v122, v58, v112
	v_mul_f32_e64 v123, v59, v112
	v_fma_f32 v38, v124, v124, v40
	v_mul_f32_e64 v140, v36, v112
	v_mul_f32_e64 v141, v37, v112
	s_nop 0
	s_nop 0
	v_fma_f32 v38, v125, v125, v38
	v_mul_f32_e64 v120, v60, v112
	v_mul_f32_e64 v121, v61, v112
	v_fma_f32 v36, v122, v122, v38
	v_mul_f32_e64 v142, v34, v112
	v_mul_f32_e64 v143, v35, v112
	s_nop 0
	s_nop 0
	v_fma_f32 v36, v123, v123, v36
	v_mul_f32_e64 v118, v62, v112
	v_mul_f32_e64 v119, v63, v112
	v_fma_f32 v34, v120, v120, v36
	v_mul_f32_e64 v144, v32, v112
	v_mul_f32_e64 v145, v33, v112
	s_nop 0
	s_nop 0
	v_fma_f32 v34, v121, v121, v34
	v_fma_f32 v32, v118, v118, v34
	s_nop 0
	s_nop 0
	v_fma_f32 v32, v119, v119, v32
	v_fma_f32 v32, v144, v144, v32
	s_nop 0
	s_nop 0
	v_fma_f32 v32, v145, v145, v32
	v_fma_f32 v32, v142, v142, v32
	s_nop 0
	s_nop 0
	v_fma_f32 v32, v143, v143, v32
	v_fma_f32 v32, v140, v140, v32
	s_nop 0
	s_nop 0
	v_fma_f32 v32, v141, v141, v32
	v_fma_f32 v32, v138, v138, v32
	s_nop 0
	s_nop 0
	v_fma_f32 v32, v139, v139, v32
	v_fma_f32 v32, v136, v136, v32
	s_nop 0
	s_nop 0
	v_fma_f32 v58, v137, v137, v32
	global_load_dwordx4 v[32:35], v[190:191], off offset:256
	global_load_dwordx4 v[36:39], v[190:191], off offset:320
	v_lshlrev_b64 v[40:41], 6, v[208:209]
	v_mul_f32_e64 v44, v44, v112
	v_mul_f32_e64 v45, v45, v112
	v_lshl_add_u64 v[60:61], v[194:195], 0, v[40:41]
	v_fma_f32 v56, v134, v134, v58
	s_nop 0
	s_nop 0
	v_lshl_add_u64 v[114:115], v[192:193], 0, v[40:41]
	global_load_dwordx4 v[40:43], v[60:61], off
	global_load_dwordx4 v[48:51], v[114:115], off
	v_fma_f32 v56, v135, v135, v56
	v_mul_f32_e64 v46, v46, v112
	v_mul_f32_e64 v47, v47, v112
	v_fma_f32 v54, v44, v44, v56
	s_nop 0
	s_nop 0
	v_fma_f32 v54, v45, v45, v54
	v_fma_f32 v52, v46, v46, v54
	v_fma_f32 v113, v47, v47, v52
	global_load_dwordx4 v[52:55], v[190:191], off offset:288
	global_load_dwordx4 v[56:59], v[190:191], off offset:352
	s_nop 0
	global_load_dwordx4 v[60:63], v[60:61], off offset:32
	s_nop 0
	global_load_dwordx4 v[114:117], v[114:115], off offset:32
	s_waitcnt vmcnt(17)
	s_nop 0
	s_nop 0
	s_nop 0
	s_nop 0
	s_waitcnt vmcnt(10)
	v_fmac_f32_e32 v113, v92, v92
	v_fmac_f32_e32 v113, v93, v93
	v_fmac_f32_e32 v113, v94, v94
	v_fmac_f32_e32 v113, v95, v95
	v_fmac_f32_e32 v113, v68, v68
	v_fmac_f32_e32 v113, v69, v69
	v_fma_f32 v113, v70, v70, v113
	v_fma_f32 v113, v71, v71, v113
	v_fma_f32 v113, v72, v72, v113
	v_fma_f32 v113, v73, v73, v113
	v_fma_f32 v113, v74, v74, v113
	v_fma_f32 v113, v75, v75, v113
	v_fma_f32 v113, v64, v64, v113
	v_fma_f32 v113, v65, v65, v113
	v_fma_f32 v113, v66, v66, v113
	v_fma_f32 v113, v67, v67, v113
	v_mov_b32_e32 v146, v113
	v_mov_b32_e32 v147, v113
	s_nop 1
	v_permlane32_swap_b32_e32 v146, v147
	v_cndmask_b32_e64 v146, v146, v147, s[8:9]
	v_add_f32_e32 v113, v113, v146
	v_fmamk_f32 v113, v113, 0x3c2aaaab, v233
	v_mul_f32_e32 v146, 0x4b800000, v113
	v_cmp_gt_f32_e32 vcc, s19, v113
	s_nop 1
	v_cndmask_b32_e32 v113, v113, v146, vcc
	v_rsq_f32_e32 v113, v113
	s_nop 0
	v_mul_f32_e32 v146, 0x45800000, v113
	v_cndmask_b32_e32 v146, v113, v146, vcc
	v_mul_f32_e64 v88, v88, v146
	v_mul_f32_e64 v89, v89, v146
	v_mul_f32_e64 v90, v90, v146
	v_mul_f32_e64 v91, v91, v146
	v_mul_f32_e64 v84, v84, v146
	v_mul_f32_e64 v85, v85, v146
	v_mul_f32_e64 v86, v86, v146
	v_mul_f32_e64 v87, v87, v146
	v_mul_f32_e64 v16, v16, v112
	v_mul_f32_e64 v17, v17, v112
	v_mul_f32_e64 v18, v18, v112
	v_mul_f32_e64 v19, v19, v112
	v_mul_f32_e64 v88, v132, v88
	v_mul_f32_e64 v89, v133, v89
	v_mul_f32_e64 v90, v130, v90
	v_mul_f32_e64 v91, v131, v91
	v_mul_f32_e64 v84, v128, v84
	v_mul_f32_e64 v85, v129, v85
	v_mul_f32_e64 v86, v126, v86
	v_mul_f32_e64 v87, v127, v87
	s_waitcnt vmcnt(8)
; DI void phase3(const Params& p, char* smem, const Sched sc) {
;     ...
; #pragma unroll
;       for (int rb = 0; rb < 2; ++rb)
; #pragma unroll
;         for (int g = 0; g < 4; ++g) {
;           const f32x4 w4 = *(const f32x4*)(p.khn + rb * 32 + 8 * g + 4 * h);
; #pragma unroll
;           for (int e = 0; e < 4; ++e) acc[rb][0][4 * g + e] *= r2 * w4[e];
;         }
; #pragma unroll
;       for (int g = 0; g < 4; ++g) {
;         const f32x4 w4 = *(const f32x4*)(p.khn + 64 + 8 * g + 4 * h);
; #pragma unroll
;         for (int e = 0; e < 4; ++e) kr[4 * g + e] *= r2 * w4[e];
;       }
; #pragma unroll
;       for (int g = 0; g < 2; ++g) {
;         const f32x4 c4 = *(const f32x4*)(p.cosT + (size_t)token * 16 + 8 * g + 4 * h), s4 = *(const f32x4*)(p.sinT + (size_t)token * 16 + 8 * g + 4 * h);
; #pragma unroll
;         for (int e = 0; e < 4; ++e) {
;           const float x1 = kr[4 * g + e], x2 = kr[4 * (g + 2) + e];
;           kr[4 * g + e] = x1 * c4[e] - x2 * s4[e];
;           kr[4 * (g + 2) + e] = x2 * c4[e] + x1 * s4[e];
;         }
;       }
	v_mul_f32_e64 v100, v100, v146
	v_mul_f32_e64 v101, v101, v146
	v_cvt_pk_bf16_f32 v16, v16, v17
	v_cvt_pk_bf16_f32 v17, v18, v19
	v_mul_f32_e64 v18, v20, v112
	v_mul_f32_e64 v19, v21, v112
	v_mul_f32_e64 v20, v22, v112
	v_mul_f32_e64 v21, v23, v112
	v_mul_f32_e64 v0, v0, v112
	v_mul_f32_e64 v1, v1, v112
	v_mul_f32_e64 v2, v2, v112
	v_mul_f32_e64 v3, v3, v112
	v_mul_f32_e64 v80, v80, v146
	v_mul_f32_e64 v81, v81, v146
	v_mul_f32_e64 v82, v82, v146
	v_mul_f32_e64 v83, v83, v146
	v_mul_f32_e64 v76, v76, v146
	v_mul_f32_e64 v77, v77, v146
	v_mul_f32_e64 v78, v78, v146
	v_mul_f32_e64 v79, v79, v146
	v_mul_f32_e64 v104, v104, v146
	v_mul_f32_e64 v105, v105, v146
	v_mul_f32_e64 v106, v106, v146
	v_mul_f32_e64 v107, v107, v146
	v_mul_f32_e64 v96, v96, v146
	v_mul_f32_e64 v97, v97, v146
	v_mul_f32_e64 v98, v98, v146
	v_mul_f32_e64 v99, v99, v146
	s_waitcnt vmcnt(7)
	v_mul_f32_e64 v32, v32, v146
	v_mul_f32_e64 v33, v33, v146
	s_waitcnt vmcnt(6)
	v_mul_f32_e64 v36, v36, v146
	v_mul_f32_e64 v37, v37, v146
	v_mul_f32_e64 v32, v92, v32
	v_mul_f32_e64 v33, v93, v33
	v_mul_f32_e64 v36, v72, v36
	v_mul_f32_e64 v37, v73, v37
	v_mul_f32_e64 v108, v108, v146
	v_mul_f32_e64 v109, v109, v146
	v_mul_f32_e64 v110, v110, v146
	v_mul_f32_e64 v111, v111, v146
	v_mul_f32_e64 v44, v44, v100
	v_mul_f32_e64 v45, v45, v101
	s_waitcnt vmcnt(5)
	v_mul_f32_e64 v72, v40, v36
	v_mul_f32_e64 v73, v41, v37
	s_waitcnt vmcnt(4)
	v_mul_f32_e64 v36, v48, v36
	v_mul_f32_e64 v37, v49, v37
	v_fma_f32 v72, v48, v32, -v72
	v_fma_f32 v73, v49, v33, -v73
	v_fma_f32 v36, v40, v32, v36
	v_fma_f32 v37, v41, v33, v37
	v_mul_f32_e64 v32, v34, v146
	v_mul_f32_e64 v33, v35, v146
	v_mul_f32_e64 v34, v38, v146
	v_mul_f32_e64 v35, v39, v146
	v_mul_f32_e64 v32, v94, v32
	v_mul_f32_e64 v33, v95, v33
	v_mul_f32_e64 v34, v74, v34
	v_mul_f32_e64 v35, v75, v35
	v_mul_f32_e64 v100, v102, v146
	v_mul_f32_e64 v101, v103, v146
	v_mul_f32_e64 v38, v42, v34
	v_mul_f32_e64 v39, v43, v35
	v_mul_f32_e64 v34, v50, v34
	v_mul_f32_e64 v35, v51, v35
	v_fma_f32 v38, v50, v32, -v38
	v_fma_f32 v39, v51, v33, -v39
	v_fma_f32 v40, v42, v32, v34
	v_fma_f32 v41, v43, v33, v35
	s_waitcnt vmcnt(2)
	v_mul_f32_e64 v34, v56, v146
	v_mul_f32_e64 v35, v57, v146
	v_mul_f32_e64 v32, v52, v146
	v_mul_f32_e64 v33, v53, v146
	v_mul_f32_e64 v34, v64, v34
	v_mul_f32_e64 v35, v65, v35
	v_mul_f32_e64 v32, v68, v32
	v_mul_f32_e64 v33, v69, v33
	s_waitcnt vmcnt(1)
	v_mul_f32_e64 v42, v60, v34
	v_mul_f32_e64 v43, v61, v35
	s_waitcnt vmcnt(0)
; DI unsigned pk_bf16(float lo, float hi) { f32x2 v = {lo, hi}; bf2_t b = __builtin_convertvector(v, bf2_t); return __builtin_bit_cast(unsigned, b); }
; DI void phase3(const Params& p, char* smem, const Sched sc) {
;     ...
;       for (int g = 0; g < 2; ++g) {
;         const f32x4 c4 = *(const f32x4*)(p.cosT + (size_t)token * 16 + 8 * g + 4 * h), s4 = *(const f32x4*)(p.sinT + (size_t)token * 16 + 8 * g + 4 * h);
; #pragma unroll
;         for (int e = 0; e < 4; ++e) {
;           const float x1 = kr[4 * g + e], x2 = kr[4 * (g + 2) + e];
;           kr[4 * g + e] = x1 * c4[e] - x2 * s4[e];
;           kr[4 * (g + 2) + e] = x2 * c4[e] + x1 * s4[e];
;         }
;       }
;       bf16_t* dk = p.Km + ((size_t)(b * 8 + head) * S_ + s) * 96;
;       bf16_t* dv = p.Vm + ((size_t)(b * 8 + head) * S_ + s) * 64;
; #pragma unroll
;       for (int rb = 0; rb < 2; ++rb) {
;         u32x2 w[4], u[4];
; #pragma unroll
;         for (int g = 0; g < 4; ++g) {
;           w[g].x = pk_bf16(acc[rb][0][4 * g], acc[rb][0][4 * g + 1]); w[g].y = pk_bf16(acc[rb][0][4 * g + 2], acc[rb][0][4 * g + 3]);
;           u[g].x = pk_bf16(acc[rb + 2][0][4 * g] * rstd, acc[rb + 2][0][4 * g + 1] * rstd); u[g].y = pk_bf16(acc[rb + 2][0][4 * g + 2] * rstd, acc[rb + 2][0][4 * g + 3] * rstd);
;         }
; #pragma unroll
;         for (int q = 0; q < 2; ++q) {
;           *(u32x4*)(dk + rb * 32 + 16 * q + 8 * h) = widen_pair(w[2 * q], w[2 * q + 1]);
;           *(u32x4*)(dv + rb * 32 + 16 * q + 8 * h) = widen_pair(u[2 * q], u[2 * q + 1]);
;         }
;       }
;       {
;         u32x2 w[4];
; #pragma unroll
;         for (int g = 0; g < 4; ++g) { w[g].x = pk_bf16(kr[4 * g], kr[4 * g + 1]); w[g].y = pk_bf16(kr[4 * g + 2], kr[4 * g + 3]); }
; #pragma unroll
;         for (int q = 0; q < 2; ++q) *(u32x4*)(dk + 64 + 16 * q + 8 * h) = widen_pair(w[2 * q], w[2 * q + 1]);
;       }
	v_mul_f32_e64 v34, v114, v34
	v_mul_f32_e64 v35, v115, v35
	v_fma_f32 v42, v114, v32, -v42
	v_fma_f32 v43, v115, v33, -v43
	v_fma_f32 v48, v60, v32, v34
	v_fma_f32 v49, v61, v33, v35
	v_mul_f32_e64 v34, v58, v146
	v_mul_f32_e64 v35, v59, v146
	v_mul_f32_e64 v32, v54, v146
	v_mul_f32_e64 v33, v55, v146
	v_mul_f32_e64 v34, v66, v34
	v_mul_f32_e64 v35, v67, v35
	v_mul_f32_e64 v32, v70, v32
	v_mul_f32_e64 v33, v71, v33
	v_mul_f32_e64 v50, v62, v34
	v_mul_f32_e64 v51, v63, v35
	v_mul_f32_e64 v34, v116, v34
	v_mul_f32_e64 v35, v117, v35
	v_fma_f32 v50, v116, v32, -v50
	v_fma_f32 v51, v117, v33, -v51
	v_fma_f32 v52, v62, v32, v34
	v_fma_f32 v53, v63, v33, v35
	v_lshl_or_b32 v32, v240, 3, s25
	v_ashrrev_i32_e32 v33, 31, v32
	v_lshlrev_b64 v[32:33], 13, v[32:33]
	v_or_b32_e32 v32, v32, v239
	v_lshlrev_b64 v[34:35], 7, v[32:33]
	v_mad_u64_u32 v[54:55], s[12:13], v32, s20, v[206:207]
	v_mad_i32_i24 v55, v33, s20, v55
	v_lshl_add_u64 v[56:57], v[196:197], 0, v[34:35]
	v_cvt_pk_bf16_f32 v32, v88, v89
	v_cvt_pk_bf16_f32 v33, v90, v91
	v_cvt_pk_bf16_f32 v34, v84, v85
	v_cvt_pk_bf16_f32 v35, v86, v87
	v_cvt_pk_bf16_f32 v18, v18, v19
	v_cvt_pk_bf16_f32 v19, v20, v21
	v_mul_f32_e64 v22, v24, v112
	v_mul_f32_e64 v23, v25, v112
	v_cvt_pk_bf16_f32 v0, v0, v1
	v_cvt_pk_bf16_f32 v1, v2, v3
	v_mul_f32_e64 v2, v4, v112
	v_mul_f32_e64 v3, v5, v112
	v_mul_f32_e64 v4, v6, v112
	v_mul_f32_e64 v5, v7, v112
	v_mul_f32_e64 v6, v8, v112
	v_mul_f32_e64 v7, v9, v112
	v_mul_f32_e64 v80, v124, v80
	v_mul_f32_e64 v81, v125, v81
	v_mul_f32_e64 v82, v122, v82
	v_mul_f32_e64 v83, v123, v83
	v_mul_f32_e64 v76, v120, v76
	v_mul_f32_e64 v77, v121, v77
	v_mul_f32_e64 v78, v118, v78
	v_mul_f32_e64 v79, v119, v79
	v_mul_f32_e64 v104, v144, v104
	v_mul_f32_e64 v105, v145, v105
	v_mul_f32_e64 v106, v142, v106
	v_mul_f32_e64 v107, v143, v107
	v_mul_f32_e64 v96, v140, v96
	v_mul_f32_e64 v97, v141, v97
	v_mul_f32_e64 v98, v138, v98
	v_mul_f32_e64 v99, v139, v99
	v_mul_f32_e64 v108, v136, v108
	v_mul_f32_e64 v109, v137, v109
	v_mul_f32_e64 v110, v134, v110
	v_mul_f32_e64 v111, v135, v111
	v_mul_f32_e64 v46, v46, v100
	v_mul_f32_e64 v47, v47, v101
	v_cvt_pk_bf16_f32 v24, v22, v23
	v_mul_f32_e64 v22, v26, v112
	v_mul_f32_e64 v23, v27, v112
	v_mul_f32_e64 v26, v28, v112
	v_mul_f32_e64 v27, v29, v112
	v_mul_f32_e64 v28, v30, v112
	v_mul_f32_e64 v29, v31, v112
	v_permlane32_swap_b32_e32 v32, v34
	v_permlane32_swap_b32_e32 v33, v35
	v_permlane32_swap_b32_e32 v16, v18
	v_permlane32_swap_b32_e32 v17, v19
	v_cvt_pk_bf16_f32 v8, v6, v7
	v_mul_f32_e64 v6, v10, v112
	v_mul_f32_e64 v7, v11, v112
	v_cvt_pk_bf16_f32 v20, v80, v81
	v_cvt_pk_bf16_f32 v21, v82, v83
	v_cvt_pk_bf16_f32 v25, v22, v23
	v_cvt_pk_bf16_f32 v22, v76, v77
	v_cvt_pk_bf16_f32 v23, v78, v79
	v_cvt_pk_bf16_f32 v26, v26, v27
	v_cvt_pk_bf16_f32 v27, v28, v29
	global_store_dwordx4 v[54:55], v[32:35], off
	global_store_dwordx4 v[56:57], v[16:19], off
	v_cvt_pk_bf16_f32 v2, v2, v3
	v_cvt_pk_bf16_f32 v3, v4, v5
	v_cvt_pk_bf16_f32 v16, v104, v105
	v_cvt_pk_bf16_f32 v17, v106, v107
	v_cvt_pk_bf16_f32 v18, v96, v97
	v_cvt_pk_bf16_f32 v19, v98, v99
	v_cvt_pk_bf16_f32 v4, v108, v109
	v_cvt_pk_bf16_f32 v5, v110, v111
	v_cvt_pk_bf16_f32 v9, v6, v7
	v_cvt_pk_bf16_f32 v6, v44, v45
	v_cvt_pk_bf16_f32 v7, v46, v47
	v_permlane32_swap_b32_e32 v20, v22
	v_permlane32_swap_b32_e32 v21, v23
	v_permlane32_swap_b32_e32 v24, v26
	v_permlane32_swap_b32_e32 v25, v27
	v_mul_f32_e64 v10, v12, v112
	v_mul_f32_e64 v11, v13, v112
	v_mul_f32_e64 v12, v14, v112
	v_mul_f32_e64 v13, v15, v112
	v_permlane32_swap_b32_e32 v16, v18
	v_permlane32_swap_b32_e32 v17, v19
	v_permlane32_swap_b32_e32 v0, v2
	v_permlane32_swap_b32_e32 v1, v3
	v_permlane32_swap_b32_e32 v4, v6
	v_permlane32_swap_b32_e32 v5, v7
	global_store_dwordx4 v[54:55], v[20:23], off offset:32
	global_store_dwordx4 v[56:57], v[24:27], off offset:32
	v_cvt_pk_bf16_f32 v10, v10, v11
	v_cvt_pk_bf16_f32 v11, v12, v13
	global_store_dwordx4 v[54:55], v[16:19], off offset:64
	global_store_dwordx4 v[56:57], v[0:3], off offset:64
	global_store_dwordx4 v[54:55], v[4:7], off offset:96
	v_permlane32_swap_b32_e32 v8, v10
	v_cvt_pk_bf16_f32 v0, v72, v73
	v_cvt_pk_bf16_f32 v1, v38, v39
	v_cvt_pk_bf16_f32 v2, v42, v43
	v_cvt_pk_bf16_f32 v3, v50, v51
	v_cvt_pk_bf16_f32 v4, v36, v37
	v_cvt_pk_bf16_f32 v5, v40, v41
	v_cvt_pk_bf16_f32 v6, v48, v49
	v_cvt_pk_bf16_f32 v7, v52, v53
	v_permlane32_swap_b32_e32 v9, v11
	v_permlane32_swap_b32_e32 v0, v2
	v_permlane32_swap_b32_e32 v1, v3
	v_permlane32_swap_b32_e32 v4, v6
	v_permlane32_swap_b32_e32 v5, v7
	global_store_dwordx4 v[56:57], v[8:11], off offset:96
	global_store_dwordx4 v[54:55], v[0:3], off offset:128
	global_store_dwordx4 v[54:55], v[4:7], off offset:160
	s_branch .LBB0_359
